# attention: QK wave drops to priority 0 after its last QK MFMA
# speedup vs baseline: 1.0078x; 1.0035x over previous
; #define SBAR() __builtin_amdgcn_sched_barrier(0)
; #define KRD(A, B, d0) do { const int ad_ = (kc ^ ((d0) << 5)) + kbt; A = lds_rd128<0>(ad_); B = lds_rd128<8192>(ad_); } while (0)
; #define KW(N) do { asm volatile("s_waitcnt lgkmcnt(" #N ")" ::: "memory"); SBAR(); } while (0)
; __device__ __forceinline__ float softmax_rel(f32x16& p0, f32x16& p1, bool first, float& m_reg, float& l_reg, bf16x8& pa0, bf16x8& pa1, bf16x8& pa2, bf16x8& pa3) {
;   float pmax = p0[0];
; #pragma unroll
;   for (int r = 1; r < 16; ++r) pmax = fmaxf(pmax, p0[r]);
; #pragma unroll
;   for (int r = 0; r < 16; ++r) pmax = fmaxf(pmax, p1[r]);
;   { auto rr = __builtin_amdgcn_permlane32_swap(__float_as_uint(pmax), __float_as_uint(pmax), false, false);
;     pmax = fmaxf(__uint_as_float(rr[0]), __uint_as_float(rr[1])); }
;   float alpha = 1.f;
;   if (__builtin_expect(first || __any(pmax > THR2), 0)) {
; __device__ __forceinline__ void qkt_pipe(f32x16& p0, f32x16& p1, int kbt, int kc, const bf16x8* qr, const f32x16& z) {
;     ...
;   KW(6); p0 = __builtin_amdgcn_mfma_f32_32x32x16_bf16(a2, qr[2], p0, 0, 0, 0); p1 = __builtin_amdgcn_mfma_f32_32x32x16_bf16(b2, qr[2], p1, 0, 0, 0); SBAR(); KRD(a2, b2, 6);
;   KW(6); p0 = __builtin_amdgcn_mfma_f32_32x32x16_bf16(a3, qr[3], p0, 0, 0, 0); p1 = __builtin_amdgcn_mfma_f32_32x32x16_bf16(b3, qr[3], p1, 0, 0, 0); SBAR(); KRD(a3, b3, 7);
;   KW(6); p0 = __builtin_amdgcn_mfma_f32_32x32x16_bf16(a0, qr[4], p0, 0, 0, 0); p1 = __builtin_amdgcn_mfma_f32_32x32x16_bf16(b0, qr[4], p1, 0, 0, 0); SBAR();
;   KW(4); p0 = __builtin_amdgcn_mfma_f32_32x32x16_bf16(a1, qr[5], p0, 0, 0, 0); p1 = __builtin_amdgcn_mfma_f32_32x32x16_bf16(b1, qr[5], p1, 0, 0, 0); SBAR();
;   KW(2); p0 = __builtin_amdgcn_mfma_f32_32x32x16_bf16(a2, qr[6], p0, 0, 0, 0); p1 = __builtin_amdgcn_mfma_f32_32x32x16_bf16(b2, qr[6], p1, 0, 0, 0); SBAR();
;   KW(0); p0 = __builtin_amdgcn_mfma_f32_32x32x16_bf16(a3, qr[7], p0, 0, 0, 0); p1 = __builtin_amdgcn_mfma_f32_32x32x16_bf16(b3, qr[7], p1, 0, 0, 0);
.Lq0_nodma:
	s_waitcnt lgkmcnt(6)
	v_mfma_f32_32x32x16_bf16 v[144:159], v[230:233], v[184:187], v[144:159]
	v_mfma_f32_32x32x16_bf16 v[128:143], v[234:237], v[184:187], v[128:143]
	v_xor_b32_e32 v220, 0xa0, v213
	v_add_u32_e32 v220, v212, v220
	ds_read_b128 v[230:233], v220 offset:0
	ds_read_b128 v[234:237], v220 offset:0x2000
	s_waitcnt lgkmcnt(6)
	v_mfma_f32_32x32x16_bf16 v[144:159], v[238:241], v[180:183], v[144:159]
	v_mfma_f32_32x32x16_bf16 v[128:143], v[242:245], v[180:183], v[128:143]
	v_xor_b32_e32 v220, 0xc0, v213
	v_add_u32_e32 v220, v212, v220
	ds_read_b128 v[238:241], v220 offset:0
	ds_read_b128 v[242:245], v220 offset:0x2000
	s_waitcnt lgkmcnt(6)
	v_mfma_f32_32x32x16_bf16 v[144:159], v[246:249], v[176:179], v[144:159]
	v_mfma_f32_32x32x16_bf16 v[128:143], v[214:217], v[176:179], v[128:143]
	v_xor_b32_e32 v214, 0xe0, v213
	v_add_u32_e32 v212, v212, v214
	ds_read_b128 v[214:217], v212 offset:0
	ds_read_b128 v[246:249], v212 offset:0x2000
	s_waitcnt lgkmcnt(6)
	v_mfma_f32_32x32x16_bf16 v[144:159], v[194:197], v[172:175], v[144:159]
	v_mfma_f32_32x32x16_bf16 v[128:143], v[226:229], v[172:175], v[128:143]
	s_waitcnt lgkmcnt(4)
	v_mfma_f32_32x32x16_bf16 v[144:159], v[230:233], v[168:171], v[144:159]
	v_mfma_f32_32x32x16_bf16 v[128:143], v[234:237], v[168:171], v[128:143]
	s_waitcnt lgkmcnt(2)
	v_mfma_f32_32x32x16_bf16 v[144:159], v[238:241], v[164:167], v[144:159]
	v_mfma_f32_32x32x16_bf16 v[128:143], v[242:245], v[164:167], v[128:143]
	s_waitcnt lgkmcnt(0)
	v_mfma_f32_32x32x16_bf16 v[144:159], v[214:217], v[160:163], v[144:159]
	s_cmp_eq_u32 s10, 0
	s_cselect_b64 s[62:63], -1, 0
	s_cmp_lg_u32 s10, 0
	v_mfma_f32_32x32x16_bf16 v[128:143], v[246:249], v[160:163], v[128:143]
	s_setprio 0
	s_nop 7
	v_max_f32_e32 v194, v145, v145
	v_max_f32_e32 v195, v144, v144
	v_max_f32_e32 v194, v195, v194
	v_max3_f32 v194, v194, v146, v147
	v_max3_f32 v194, v194, v148, v149
	v_max3_f32 v195, v128, v129, v130
	v_max3_f32 v194, v194, v150, v151
	v_max3_f32 v195, v195, v131, v132
	v_max3_f32 v194, v194, v152, v153
	v_max3_f32 v195, v195, v133, v134
	v_max3_f32 v194, v194, v154, v155
	v_max3_f32 v195, v195, v135, v136
	v_max3_f32 v194, v194, v156, v157
	v_max3_f32 v195, v195, v137, v138
	v_max3_f32 v194, v194, v158, v159
	v_max3_f32 v195, v195, v139, v140
	v_max3_f32 v195, v195, v141, v142
	v_max3_f32 v194, v194, v195, v143
	v_mov_b32_e32 v195, v194
	s_nop 1
	v_permlane32_swap_b32_e32 v194, v195
	v_max_f32_e32 v195, v195, v195
	v_max_f32_e32 v194, v194, v194
	v_max_f32_e32 v226, v194, v195
	s_cbranch_scc0 .LBB0_371
	v_cmp_lt_f32_e32 vcc, s30, v226
	s_cbranch_vccnz .Lm0_rare
	v_mov_b32_e32 v226, 1.0

; #define SBAR() __builtin_amdgcn_sched_barrier(0)
; #define KRD(A, B, d0) do { const int ad_ = (kc ^ ((d0) << 5)) + kbt; A = lds_rd128<0>(ad_); B = lds_rd128<8192>(ad_); } while (0)
; #define KW(N) do { asm volatile("s_waitcnt lgkmcnt(" #N ")" ::: "memory"); SBAR(); } while (0)
; __device__ __forceinline__ float softmax_rel(f32x16& p0, f32x16& p1, bool first, float& m_reg, float& l_reg, bf16x8& pa0, bf16x8& pa1, bf16x8& pa2, bf16x8& pa3) {
;   float pmax = p0[0];
; #pragma unroll
;   for (int r = 1; r < 16; ++r) pmax = fmaxf(pmax, p0[r]);
; #pragma unroll
;   for (int r = 0; r < 16; ++r) pmax = fmaxf(pmax, p1[r]);
;   { auto rr = __builtin_amdgcn_permlane32_swap(__float_as_uint(pmax), __float_as_uint(pmax), false, false);
;     pmax = fmaxf(__uint_as_float(rr[0]), __uint_as_float(rr[1])); }
;   float alpha = 1.f;
;   if (__builtin_expect(first || __any(pmax > THR2), 0)) {
; __device__ __forceinline__ void qkt_pipe(f32x16& p0, f32x16& p1, int kbt, int kc, const bf16x8* qr, const f32x16& z) {
;     ...
;   KW(6); p0 = __builtin_amdgcn_mfma_f32_32x32x16_bf16(a2, qr[2], p0, 0, 0, 0); p1 = __builtin_amdgcn_mfma_f32_32x32x16_bf16(b2, qr[2], p1, 0, 0, 0); SBAR(); KRD(a2, b2, 6);
;   KW(6); p0 = __builtin_amdgcn_mfma_f32_32x32x16_bf16(a3, qr[3], p0, 0, 0, 0); p1 = __builtin_amdgcn_mfma_f32_32x32x16_bf16(b3, qr[3], p1, 0, 0, 0); SBAR(); KRD(a3, b3, 7);
;   KW(6); p0 = __builtin_amdgcn_mfma_f32_32x32x16_bf16(a0, qr[4], p0, 0, 0, 0); p1 = __builtin_amdgcn_mfma_f32_32x32x16_bf16(b0, qr[4], p1, 0, 0, 0); SBAR();
;   KW(4); p0 = __builtin_amdgcn_mfma_f32_32x32x16_bf16(a1, qr[5], p0, 0, 0, 0); p1 = __builtin_amdgcn_mfma_f32_32x32x16_bf16(b1, qr[5], p1, 0, 0, 0); SBAR();
;   KW(2); p0 = __builtin_amdgcn_mfma_f32_32x32x16_bf16(a2, qr[6], p0, 0, 0, 0); p1 = __builtin_amdgcn_mfma_f32_32x32x16_bf16(b2, qr[6], p1, 0, 0, 0); SBAR();
;   KW(0); p0 = __builtin_amdgcn_mfma_f32_32x32x16_bf16(a3, qr[7], p0, 0, 0, 0); p1 = __builtin_amdgcn_mfma_f32_32x32x16_bf16(b3, qr[7], p1, 0, 0, 0);
.Lq1_nodma:
	s_waitcnt lgkmcnt(6)
	v_mfma_f32_32x32x16_bf16 v[144:159], v[230:233], v[184:187], v[144:159]
	v_mfma_f32_32x32x16_bf16 v[128:143], v[234:237], v[184:187], v[128:143]
	v_xor_b32_e32 v229, 0xa0, v225
	v_add_u32_e32 v229, v212, v229
	ds_read_b128 v[230:233], v229 offset:0
	ds_read_b128 v[234:237], v229 offset:0x2000
	s_waitcnt lgkmcnt(6)
	v_mfma_f32_32x32x16_bf16 v[144:159], v[238:241], v[180:183], v[144:159]
	v_mfma_f32_32x32x16_bf16 v[128:143], v[242:245], v[180:183], v[128:143]
	v_xor_b32_e32 v229, 0xc0, v225
	v_add_u32_e32 v229, v212, v229
	ds_read_b128 v[238:241], v229 offset:0
	ds_read_b128 v[242:245], v229 offset:0x2000
	s_waitcnt lgkmcnt(6)
	v_mfma_f32_32x32x16_bf16 v[144:159], v[246:249], v[176:179], v[144:159]
	v_mfma_f32_32x32x16_bf16 v[128:143], v[220:223], v[176:179], v[128:143]
	v_xor_b32_e32 v220, 0xe0, v225
	v_add_u32_e32 v212, v212, v220
	ds_read_b128 v[220:223], v212 offset:0
	ds_read_b128 v[246:249], v212 offset:0x2000
	s_waitcnt lgkmcnt(6)
	v_mfma_f32_32x32x16_bf16 v[144:159], v[194:197], v[172:175], v[144:159]
	v_mfma_f32_32x32x16_bf16 v[128:143], v[214:217], v[172:175], v[128:143]
	s_waitcnt lgkmcnt(4)
	v_mfma_f32_32x32x16_bf16 v[144:159], v[230:233], v[168:171], v[144:159]
	v_mfma_f32_32x32x16_bf16 v[128:143], v[234:237], v[168:171], v[128:143]
	s_waitcnt lgkmcnt(2)
	v_mfma_f32_32x32x16_bf16 v[144:159], v[238:241], v[164:167], v[144:159]
	v_mfma_f32_32x32x16_bf16 v[128:143], v[242:245], v[164:167], v[128:143]
	s_waitcnt lgkmcnt(0)
	v_mfma_f32_32x32x16_bf16 v[144:159], v[220:223], v[160:163], v[144:159]
	s_cmp_eq_u32 s9, 0
	s_cselect_b64 s[56:57], -1, 0
	s_cmp_lg_u32 s9, 0
	v_mfma_f32_32x32x16_bf16 v[128:143], v[246:249], v[160:163], v[128:143]
	s_setprio 0
	s_nop 7
	v_max_f32_e32 v194, v145, v145
	v_max_f32_e32 v195, v144, v144
	v_max_f32_e32 v194, v195, v194
	v_max3_f32 v194, v194, v146, v147
	v_max3_f32 v194, v194, v148, v149
	v_max3_f32 v195, v128, v129, v130
	v_max3_f32 v194, v194, v150, v151
	v_max3_f32 v195, v195, v131, v132
	v_max3_f32 v194, v194, v152, v153
	v_max3_f32 v195, v195, v133, v134
	v_max3_f32 v194, v194, v154, v155
	v_max3_f32 v195, v195, v135, v136
	v_max3_f32 v194, v194, v156, v157
	v_max3_f32 v195, v195, v137, v138
	v_max3_f32 v194, v194, v158, v159
	v_max3_f32 v195, v195, v139, v140
	v_max3_f32 v195, v195, v141, v142
	v_max3_f32 v194, v194, v195, v143
	v_mov_b32_e32 v195, v194
	s_nop 1
	v_permlane32_swap_b32_e32 v194, v195
	v_max_f32_e32 v195, v195, v195
	v_max_f32_e32 v194, v194, v194
	v_max_f32_e32 v229, v194, v195
	s_cbranch_scc0 .LBB0_404
	v_cmp_lt_f32_e32 vcc, s30, v229
	s_cbranch_vccnz .Lm1_rare
	v_mov_b32_e32 v229, 1.0
